# mla_row: kv-latent and silu slices requested at the top of the row with the q-latent slice; rotary stage issues its three loads together (was five serial load-wait steps per row)
# speedup vs baseline: 1.0089x; 1.0089x over previous
; DI void unpack8(u32x4 w, float* v) { v[0] = lo16(w.x); v[1] = hi16(w.x); v[2] = lo16(w.y); v[3] = hi16(w.y); v[4] = lo16(w.z); v[5] = hi16(w.z); v[6] = lo16(w.w); v[7] = hi16(w.w); }
; DI u32x4 pack8(const float* v) { u32x4 w; w.x = pk2(v[0], v[1]); w.y = pk2(v[2], v[3]); w.z = pk2(v[4], v[5]); w.w = pk2(v[6], v[7]); return w; }
; DI float wave_sum(float v) { for (int o = 32; o >= 1; o >>= 1) v += __shfl_xor(v, o); return v; }
; DI void mla_row(CP c, int l, int r, int lane) {
;     unsigned char* ws = c->ws; const bf16_t* z = (const bf16_t*)(ws + WS_Z1) + (size_t)r * NZ1;
;     const bool samp = r >= MP; const int b = (r - MP) >> 4, t = (r - MP) & 15;
;     {
;         float v[8]; float ss = 0.f;
;         if (lane < 48) { unpack8(*(const u32x4*)(z + 3080 + lane * 8), v);
; #pragma unroll
;             for (int j = 0; j < 8; ++j) ss += v[j] * v[j]; }
;         const float rs = rsqrtf(wave_sum(ss) * (1.f / 384.f) + 1e-6f);
;         if (lane < 48) { const float* g = c->in[I_QNG] + l * 384 + lane * 8;
; #pragma unroll
;             for (int j = 0; j < 8; ++j) v[j] = v[j] * rs * g[j];
;             *(u32x4*)((bf16_t*)(ws + WS_QN) + (size_t)r * 384 + lane * 8) = pack8(v); }
;     }
.LBB0_1052:
	v_mov_b32_e32 v0, 0
	v_lshl_add_u64 v[38:39], s[20:21], 0, v[32:33]
	s_mov_b32 s88, 0x2e55000
	s_mov_b32 s89, 0
	v_lshl_add_u64 v[64:65], v[38:39], 0, s[88:89]
	global_load_dwordx4 v[74:77], v[64:65], off offset:2832
	global_load_dwordx4 v[70:73], v[64:65], off offset:1024
	v_mov_b32_e32 v2, 0
	v_mov_b32_e32 v3, 0
	v_mov_b32_e32 v6, 0
	v_mov_b32_e32 v7, 0
	v_mov_b32_e32 v4, 0
	v_mov_b32_e32 v5, 0
	v_mov_b32_e32 v8, 0
	v_mov_b32_e32 v9, 0
	s_and_saveexec_b64 s[18:19], s[38:39]
	s_cbranch_execz .LBB0_1054
	v_add_co_u32_e32 v2, vcc, 0x2e55000, v38
	s_nop 1
	v_addc_co_u32_e32 v3, vcc, 0, v39, vcc
	global_load_dwordx4 v[4:7], v[2:3], off offset:2064
	s_waitcnt vmcnt(0)
	v_lshlrev_b32_e32 v2, 16, v4
	v_and_b32_e32 v3, 0xffff0000, v4
	v_and_b32_e32 v4, 0xffff0000, v5
	v_lshlrev_b32_e32 v5, 16, v5
	v_pk_mul_f32 v[40:41], v[2:3], v[2:3]
	v_pk_mul_f32 v[48:49], v[4:5], v[4:5]
	v_add_f32_e32 v0, v40, v41
	v_and_b32_e32 v8, 0xffff0000, v6
	v_lshlrev_b32_e32 v9, 16, v6
	v_add_f32_e32 v0, v49, v0
	v_pk_mul_f32 v[50:51], v[8:9], v[8:9]
	v_add_f32_e32 v0, v48, v0
	v_and_b32_e32 v36, 0xffff0000, v7
	v_lshlrev_b32_e32 v37, 16, v7
	v_add_f32_e32 v0, v51, v0
	v_pk_mov_b32 v[6:7], v[4:5], v[4:5] op_sel:[1,0]
	v_pk_mov_b32 v[4:5], v[8:9], v[8:9] op_sel:[1,0]
	v_pk_mov_b32 v[8:9], v[36:37], v[36:37] op_sel:[1,0]
	v_pk_mul_f32 v[36:37], v[36:37], v[36:37]
	v_add_f32_e32 v0, v50, v0
	v_add_f32_e32 v0, v37, v0
	v_add_f32_e32 v0, v36, v0

; DI void unpack8(u32x4 w, float* v) { v[0] = lo16(w.x); v[1] = hi16(w.x); v[2] = lo16(w.y); v[3] = hi16(w.y); v[4] = lo16(w.z); v[5] = hi16(w.z); v[6] = lo16(w.w); v[7] = hi16(w.w); }
; DI float wave_sum(float v) { for (int o = 32; o >= 1; o >>= 1) v += __shfl_xor(v, o); return v; }
; DI void mla_row(CP c, int l, int r, int lane) {
;     ...
;     {
;         float v[8]; float ss = 0.f;
;         if (lane < 32) { unpack8(*(const u32x4*)(z + 3464 + lane * 8), v);
; #pragma unroll
;             for (int j = 0; j < 8; ++j) ss += v[j] * v[j]; }
;         const float rs = rsqrtf(wave_sum(ss) * (1.f / 256.f) + 1e-6f);
.LBB0_1056:
	s_or_b64 exec, exec, s[18:19]
	v_mov_b32_e32 v0, 0
	v_mov_b32_e32 v2, 0
	v_mov_b32_e32 v3, 0
	v_mov_b32_e32 v6, 0
	v_mov_b32_e32 v7, 0
	v_mov_b32_e32 v4, 0
	v_mov_b32_e32 v5, 0
	v_mov_b32_e32 v8, 0
	v_mov_b32_e32 v9, 0
	s_and_saveexec_b64 s[18:19], s[40:41]
	s_cbranch_execz .LBB0_1058
	v_add_co_u32_e32 v2, vcc, 0x2e55000, v38
	s_nop 1
	v_addc_co_u32_e32 v3, vcc, 0, v39, vcc
	v_mov_b32_e32 v4, v74
	v_mov_b32_e32 v5, v75
	v_mov_b32_e32 v6, v76
	v_mov_b32_e32 v7, v77
	v_lshlrev_b32_e32 v2, 16, v4
	v_and_b32_e32 v3, 0xffff0000, v4
	v_and_b32_e32 v4, 0xffff0000, v5
	v_lshlrev_b32_e32 v5, 16, v5
	v_pk_mul_f32 v[40:41], v[2:3], v[2:3]
	v_pk_mul_f32 v[48:49], v[4:5], v[4:5]
	v_add_f32_e32 v0, v40, v41
	v_and_b32_e32 v8, 0xffff0000, v6
	v_lshlrev_b32_e32 v9, 16, v6
	v_add_f32_e32 v0, v49, v0
	v_pk_mul_f32 v[50:51], v[8:9], v[8:9]
	v_add_f32_e32 v0, v48, v0
	v_and_b32_e32 v36, 0xffff0000, v7
	v_lshlrev_b32_e32 v37, 16, v7
	v_add_f32_e32 v0, v51, v0
	v_pk_mov_b32 v[6:7], v[4:5], v[4:5] op_sel:[1,0]
	v_pk_mov_b32 v[4:5], v[8:9], v[8:9] op_sel:[1,0]
	v_pk_mov_b32 v[8:9], v[36:37], v[36:37] op_sel:[1,0]
	v_pk_mul_f32 v[36:37], v[36:37], v[36:37]
	v_add_f32_e32 v0, v50, v0
	v_add_f32_e32 v0, v37, v0
	v_add_f32_e32 v0, v36, v0

; DI float bf2f(bf16_t b) { return __uint_as_float(((unsigned)b) << 16); }
; DI bf16_t f2bf(float f) { unsigned u = __float_as_uint(f); u += 0x7FFFu + ((u >> 16) & 1u); return (bf16_t)(u >> 16); }
; DI void mla_row(CP c, int l, int r, int lane) {
;     ...
;     if (lane < 32) {
;         const float x1 = bf2f(z[3720 + lane]), x2 = bf2f(z[3752 + lane]); const int pos = samp ? 2048 + t : r;
;         const float* cs = (const float*)(ws + WS_ROPE) + ((size_t)pos * 32 + lane) * 2; const float co = cs[0], si = cs[1];
;         const float o1 = x1 * co - x2 * si, o2 = x2 * co + x1 * si;
;         bf16_t* kp = (bf16_t*)(ws + WS_KPE) + (size_t)r * 64; kp[lane] = f2bf(o1); kp[32 + lane] = f2bf(o2);
.LBB0_1065:
	s_or_b64 exec, exec, s[24:25]
	v_lshl_add_u64 v[2:3], s[20:21], 0, v[30:31]
	v_add_co_u32_e32 v2, vcc, 0x2e55000, v2
	s_movk_i32 s14, 0x7fff
	s_nop 0
	v_addc_co_u32_e32 v3, vcc, 0, v3, vcc
	global_load_ushort v0, v[2:3], off offset:3344
	global_load_ushort v84, v[2:3], off offset:3408
	v_or_b32_e32 v2, 0x800, v11
	v_cndmask_b32_e64 v2, v10, v2, s[42:43]
	v_ashrrev_i32_e32 v3, 31, v2
	v_lshlrev_b64 v[2:3], 8, v[2:3]
	v_lshl_add_u64 v[2:3], v[16:17], 0, v[2:3]
	global_load_dwordx2 v[2:3], v[2:3], off
	s_waitcnt vmcnt(0)
	v_lshlrev_b32_e32 v0, 16, v0
	v_lshlrev_b32_e32 v5, 16, v84
	v_mul_f32_e32 v4, v3, v5
	v_mul_f32_e32 v5, v2, v5
	v_fma_f32 v4, v2, v0, -v4
	v_fmac_f32_e32 v5, v3, v0
	v_lshl_add_u64 v[2:3], s[20:21], 0, v[22:23]
	v_bfe_u32 v0, v4, 16, 1
	v_add_co_u32_e32 v2, vcc, 0x121b4000, v2
	v_add3_u32 v0, v4, v0, s14
	s_nop 0
	v_addc_co_u32_e32 v3, vcc, 0, v3, vcc
	global_store_short_d16_hi v[2:3], v0, off
	v_bfe_u32 v0, v5, 16, 1
	v_add3_u32 v0, v5, v0, s14
	global_store_short_d16_hi v[2:3], v0, off offset:64
	s_and_saveexec_b64 s[24:25], s[44:45]
	s_xor_b64 s[24:25], exec, s[24:25]
	s_cbranch_execz .LBB0_1067
	s_waitcnt lgkmcnt(0)
	v_lshl_add_u64 v[2:3], s[22:23], 0, v[20:21]

; DI float bf2f(bf16_t b) { return __uint_as_float(((unsigned)b) << 16); }
; DI void unpack8(u32x4 w, float* v) { v[0] = lo16(w.x); v[1] = hi16(w.x); v[2] = lo16(w.y); v[3] = hi16(w.y); v[4] = lo16(w.z); v[5] = hi16(w.z); v[6] = lo16(w.w); v[7] = hi16(w.w); }
; DI u32x4 pack8(const float* v) { u32x4 w; w.x = pk2(v[0], v[1]); w.y = pk2(v[2], v[3]); w.z = pk2(v[4], v[5]); w.w = pk2(v[6], v[7]); return w; }
; DI float silu(float x) { return x * __builtin_amdgcn_rcpf(1.f + fexp(-x)); }
; DI void mla_row(CP c, int l, int r, int lane) {
;     ...
;     {
;         float v[8]; unpack8(*(const u32x4*)(z + 2560 + lane * 8), v);
; #pragma unroll
;         for (int j = 0; j < 8; ++j) v[j] = silu(v[j]);
;         *(u32x4*)((bf16_t*)(ws + WS_SZ) + (size_t)r * 512 + lane * 8) = pack8(v);
;     }
;     float* gco = nullptr;
;     if (!samp && r >= MP - 3) gco = c->out + O_PGC + ((size_t)l * 3 + (r - (MP - 3))) * 1536;
;     if (samp && t >= 13) gco = c->out + O_SGC + ((size_t)(l * 32 + b) * 3 + (t - 13)) * 1536;
;     if (gco) for (int i = 0; i < 24; ++i) gco[lane + 64 * i] = bf2f(z[1024 + lane + 64 * i]);
.LBB0_1070:
	s_or_b64 exec, exec, s[18:19]
	v_add_co_u32_e32 v2, vcc, 0x2e55000, v38
	s_movk_i32 s14, 0x3ffc
	s_nop 0
	v_addc_co_u32_e32 v3, vcc, 0, v39, vcc
	v_mov_b32_e32 v2, v70
	v_mov_b32_e32 v3, v71
	v_mov_b32_e32 v4, v72
	v_mov_b32_e32 v5, v73
	v_cmp_lt_i32_e32 vcc, s14, v10
	s_xor_b64 s[18:19], s[42:43], vcc
	s_waitcnt vmcnt(0)
	v_lshlrev_b32_e32 v6, 16, v2
	v_mul_f32_e32 v0, 0xbfb8aa3b, v6
	v_exp_f32_e32 v0, v0
	v_and_b32_e32 v7, 0xffff0000, v2
	v_lshlrev_b32_e32 v2, 16, v3
	v_and_b32_e32 v3, 0xffff0000, v3
	v_add_f32_e32 v0, 1.0, v0
	v_rcp_f32_e32 v8, v0
	v_mul_f32_e32 v0, 0xbfb8aa3b, v7
	v_exp_f32_e32 v0, v0
	s_nop 0
	v_add_f32_e32 v0, 1.0, v0
	v_rcp_f32_e32 v9, v0
	v_mul_f32_e32 v0, 0xbfb8aa3b, v2
	v_exp_f32_e32 v0, v0
	v_pk_mul_f32 v[6:7], v[8:9], v[6:7]
	v_add_f32_e32 v0, 1.0, v0
	v_rcp_f32_e32 v8, v0
	v_mul_f32_e32 v0, 0xbfb8aa3b, v3
	v_exp_f32_e32 v0, v0
	s_nop 0
	v_add_f32_e32 v0, 1.0, v0
	v_rcp_f32_e32 v9, v0
	s_nop 0
	v_pk_mul_f32 v[8:9], v[8:9], v[2:3]
	v_lshlrev_b32_e32 v2, 16, v4
	v_mul_f32_e32 v0, 0xbfb8aa3b, v2
	v_exp_f32_e32 v0, v0
	v_and_b32_e32 v3, 0xffff0000, v4
	v_add_f32_e32 v0, 1.0, v0
	v_rcp_f32_e32 v38, v0
	v_mul_f32_e32 v0, 0xbfb8aa3b, v3
	v_exp_f32_e32 v0, v0
	s_nop 0
	v_add_f32_e32 v0, 1.0, v0
	v_rcp_f32_e32 v39, v0
	s_nop 0
	v_pk_mul_f32 v[38:39], v[38:39], v[2:3]
	v_lshlrev_b32_e32 v2, 16, v5
	v_mul_f32_e32 v0, 0xbfb8aa3b, v2
	v_exp_f32_e32 v0, v0
	v_and_b32_e32 v3, 0xffff0000, v5
	v_add_f32_e32 v0, 1.0, v0
	v_rcp_f32_e32 v4, v0
	v_mul_f32_e32 v0, 0xbfb8aa3b, v3
	v_exp_f32_e32 v0, v0
	s_nop 0
	v_add_f32_e32 v0, 1.0, v0
	v_rcp_f32_e32 v5, v0
	s_nop 0
	v_pk_mul_f32 v[40:41], v[4:5], v[2:3]
	v_cvt_pk_bf16_f32 v2, v6, v7
	v_cvt_pk_bf16_f32 v3, v8, v9
	v_cvt_pk_bf16_f32 v4, v38, v39
	v_cvt_pk_bf16_f32 v5, v40, v41
	v_lshl_add_u64 v[6:7], s[20:21], 0, v[28:29]
	global_store_dwordx4 v[6:7], v[2:5], off
	s_nop 1
	v_mov_b64_e32 v[2:3], 0
	s_waitcnt lgkmcnt(0)
	s_and_saveexec_b64 s[22:23], s[18:19]
	s_cbranch_execz .LBB0_1072
	s_load_dwordx2 s[18:19], s[46:47], 0x128
	v_add_u32_e32 v0, 0xffffc003, v10
	v_lshl_add_u64 v[2:3], v[0:1], 0, s[6:7]
	s_movk_i32 s14, 0x1800
	s_waitcnt lgkmcnt(0)
	v_mov_b64_e32 v[4:5], s[18:19]
	v_mad_u64_u32 v[4:5], s[18:19], v2, s14, v[4:5]
	v_mad_i32_i24 v5, v3, s14, v5
	s_mov_b64 s[18:19], 0x6a1e000
	v_lshl_add_u64 v[2:3], v[4:5], 0, s[18:19]
